# FFN-out x4 gated epilogue: the two serialized pairs of gate-vector loads issued together (one round trip per unit instead of two)
# speedup vs baseline: 1.0032x; 1.0007x over previous
;     __device__ __forceinline__ void operator()(const f32x4 (&acc)[2][2][4][2], const Unit& u, int wr, int wc, int fr, int fq) const {
;     ...
;         const float* gp = gate + (size_t)mrow * 18432 + col0;
;         f32x4 gv[2][2];
; #pragma unroll
;         for (int bj = 0; bj < 2; ++bj)
; #pragma unroll
;             for (int n = 0; n < 2; ++n) gv[bj][n] = *(const f32x4*)(gp + bj * HALF + 4 * n) * coef;
;         bf16_t* dbase = D + ((size_t)u.pm * BM + rloc0) * 2048 + col0;
.LBB0_413:
	s_mul_i32 s4, s12, 33
	s_sub_i32 s4, s34, s4
	s_cmp_lg_u32 s4, 0
	s_cselect_b32 s4, s12, 2
	s_mul_hi_i32 s5, s4, 0x12000
	s_mul_i32 s4, s4, 0x12000
	s_add_u32 s4, s3, s4
	s_addc_u32 s5, s44, s5
	v_lshl_add_u64 v[170:171], v[174:175], 2, s[4:5]
	global_load_dwordx4 v[166:169], v[170:171], off offset:16
	global_load_dwordx4 v[158:161], v[170:171], off
	global_load_dwordx4 v[180:183], v[170:171], off offset:528
	global_load_dwordx4 v[244:247], v[170:171], off offset:512
	s_ashr_i32 s35, s34, 31
	s_lshl_b64 s[4:5], s[34:35], 20
	s_waitcnt vmcnt(2)
	v_pk_mul_f32 v[162:163], v[160:161], 0.5 op_sel_hi:[1,0]
	v_pk_mul_f32 v[164:165], v[158:159], 0.5 op_sel_hi:[1,0]
	v_pk_mul_f32 v[158:159], v[168:169], 0.5 op_sel_hi:[1,0]
	v_pk_mul_f32 v[160:161], v[166:167], 0.5 op_sel_hi:[1,0]


; __device__ __forceinline__ unsigned cvt_pk_bf16(float lo, float hi) { unsigned r; asm volatile("v_cvt_pk_bf16_f32 %0, %1, %2" : "=v"(r) : "v"(lo), "v"(hi)); return r; }
;     __device__ __forceinline__ void operator()(const f32x4 (&acc)[2][2][4][2], const Unit& u, int wr, int wc, int fr, int fq) const {
;     ...
;             for (int n = 0; n < 2; ++n) gv[bj][n] = *(const f32x4*)(gp + bj * HALF + 4 * n) * coef;
;         bf16_t* dbase = D + ((size_t)u.pm * BM + rloc0) * 2048 + col0;
; #pragma unroll
;         for (int ai = 0; ai < 2; ++ai)
; #pragma unroll
;             for (int m = 0; m < 4; ++m)
; #pragma unroll
;                 for (int bj = 0; bj < 2; ++bj) { const f32x4 v0 = gv[bj][0] * acc[ai][bj][m][0], v1 = gv[bj][1] * acc[ai][bj][m][1];
;                     u32x4 w; w.x = cvt_pk_bf16(v0[0], v0[1]); w.y = cvt_pk_bf16(v0[2], v0[3]); w.z = cvt_pk_bf16(v1[0], v1[1]); w.w = cvt_pk_bf16(v1[2], v1[3]);
;                     *(u32x4*)(dbase + (size_t)(ai * HALF + m * 16) * 2048 + bj * HALF) = w; }
	v_pk_mul_f32 v[186:187], v[122:123], v[158:159]
	v_pk_mul_f32 v[188:189], v[120:121], v[160:161]
	s_waitcnt vmcnt(0)
	v_pk_mul_f32 v[170:171], v[246:247], 0.5 op_sel_hi:[1,0]
	v_pk_mul_f32 v[168:169], v[180:181], 0.5 op_sel_hi:[1,0]
	v_lshl_add_u64 v[180:181], v[152:153], 0, s[4:5]
	v_pk_mul_f32 v[172:173], v[244:245], 0.5 op_sel_hi:[1,0]
	v_pk_mul_f32 v[166:167], v[182:183], 0.5 op_sel_hi:[1,0]
	v_lshl_add_u64 v[174:175], v[174:175], 1, v[180:181]
	v_pk_mul_f32 v[182:183], v[126:127], v[162:163]
	v_pk_mul_f32 v[180:181], v[124:125], v[164:165]
	s_mov_b32 s4, 0x10000
	v_cvt_pk_bf16_f32 v180, v180, v181
	v_cvt_pk_bf16_f32 v181, v182, v183
	v_cvt_pk_bf16_f32 v182, v188, v189
	v_cvt_pk_bf16_f32 v183, v186, v187
	global_store_dwordx4 v[174:175], v[180:183], off
	v_pk_mul_f32 v[186:187], v[90:91], v[166:167]
	v_pk_mul_f32 v[188:189], v[88:89], v[168:169]
	v_pk_mul_f32 v[182:183], v[94:95], v[170:171]
	v_pk_mul_f32 v[180:181], v[92:93], v[172:173]
	v_pk_mul_f32 v[190:191], v[80:81], v[168:169]
	v_cvt_pk_bf16_f32 v180, v180, v181
	v_cvt_pk_bf16_f32 v181, v182, v183
	v_cvt_pk_bf16_f32 v182, v188, v189
	v_cvt_pk_bf16_f32 v183, v186, v187
	global_store_dwordx4 v[174:175], v[180:183], off offset:256
	v_pk_mul_f32 v[186:187], v[114:115], v[158:159]
	v_pk_mul_f32 v[188:189], v[112:113], v[160:161]
	v_pk_mul_f32 v[182:183], v[118:119], v[162:163]
	v_pk_mul_f32 v[180:181], v[116:117], v[164:165]
	s_nop 0
	v_cvt_pk_bf16_f32 v180, v180, v181
	v_cvt_pk_bf16_f32 v181, v182, v183
	v_cvt_pk_bf16_f32 v182, v188, v189
	v_cvt_pk_bf16_f32 v183, v186, v187
	v_add_co_u32_e32 v186, vcc, s4, v174
	v_pk_mul_f32 v[188:189], v[82:83], v[166:167]
	s_nop 0
	v_addc_co_u32_e32 v187, vcc, 0, v175, vcc
	global_store_dwordx4 v[186:187], v[180:183], off
	s_mov_b32 s4, 0x20000
	s_nop 0
	v_pk_mul_f32 v[182:183], v[86:87], v[170:171]
	v_pk_mul_f32 v[180:181], v[84:85], v[172:173]
	s_nop 0
	v_cvt_pk_bf16_f32 v180, v180, v181
	v_cvt_pk_bf16_f32 v181, v182, v183
	v_cvt_pk_bf16_f32 v182, v190, v191
	v_cvt_pk_bf16_f32 v183, v188, v189
	global_store_dwordx4 v[186:187], v[180:183], off offset:256
	v_pk_mul_f32 v[186:187], v[106:107], v[158:159]
	v_pk_mul_f32 v[188:189], v[104:105], v[160:161]
	v_pk_mul_f32 v[182:183], v[110:111], v[162:163]
	v_pk_mul_f32 v[180:181], v[108:109], v[164:165]
	v_pk_mul_f32 v[190:191], v[72:73], v[168:169]
	v_cvt_pk_bf16_f32 v180, v180, v181
	v_cvt_pk_bf16_f32 v181, v182, v183
	v_cvt_pk_bf16_f32 v182, v188, v189
	v_cvt_pk_bf16_f32 v183, v186, v187
	v_add_co_u32_e32 v186, vcc, s4, v174
	v_pk_mul_f32 v[188:189], v[74:75], v[166:167]
	s_nop 0
	v_addc_co_u32_e32 v187, vcc, 0, v175, vcc
	global_store_dwordx4 v[186:187], v[180:183], off
	s_mov_b32 s4, 0x30000
	s_nop 0
	v_pk_mul_f32 v[182:183], v[78:79], v[170:171]
	v_pk_mul_f32 v[180:181], v[76:77], v[172:173]
	s_nop 0
	v_cvt_pk_bf16_f32 v180, v180, v181
	v_cvt_pk_bf16_f32 v181, v182, v183
	v_cvt_pk_bf16_f32 v182, v190, v191
	v_cvt_pk_bf16_f32 v183, v188, v189
	global_store_dwordx4 v[186:187], v[180:183], off offset:256
	v_pk_mul_f32 v[186:187], v[98:99], v[158:159]
	v_pk_mul_f32 v[188:189], v[96:97], v[160:161]
	v_pk_mul_f32 v[182:183], v[102:103], v[162:163]
	v_pk_mul_f32 v[180:181], v[100:101], v[164:165]
	v_pk_mul_f32 v[190:191], v[64:65], v[168:169]
	v_cvt_pk_bf16_f32 v180, v180, v181
	v_cvt_pk_bf16_f32 v181, v182, v183
	v_cvt_pk_bf16_f32 v182, v188, v189
	v_cvt_pk_bf16_f32 v183, v186, v187
	v_add_co_u32_e32 v186, vcc, s4, v174
	v_pk_mul_f32 v[188:189], v[66:67], v[166:167]
	s_nop 0
	v_addc_co_u32_e32 v187, vcc, 0, v175, vcc
	global_store_dwordx4 v[186:187], v[180:183], off
	s_mov_b32 s4, 0x80000
	s_nop 0
	v_pk_mul_f32 v[182:183], v[70:71], v[170:171]
	v_pk_mul_f32 v[180:181], v[68:69], v[172:173]
	s_nop 0
	v_cvt_pk_bf16_f32 v180, v180, v181
; __device__ __forceinline__ unsigned cvt_pk_bf16(float lo, float hi) { unsigned r; asm volatile("v_cvt_pk_bf16_f32 %0, %1, %2" : "=v"(r) : "v"(lo), "v"(hi)); return r; }
;     __device__ __forceinline__ void operator()(const f32x4 (&acc)[2][2][4][2], const Unit& u, int wr, int wc, int fr, int fq) const {
;     ...
; #pragma unroll
;         for (int ai = 0; ai < 2; ++ai)
; #pragma unroll
;             for (int m = 0; m < 4; ++m)
; #pragma unroll
;                 for (int bj = 0; bj < 2; ++bj) { const f32x4 v0 = gv[bj][0] * acc[ai][bj][m][0], v1 = gv[bj][1] * acc[ai][bj][m][1];
;                     u32x4 w; w.x = cvt_pk_bf16(v0[0], v0[1]); w.y = cvt_pk_bf16(v0[2], v0[3]); w.z = cvt_pk_bf16(v1[0], v1[1]); w.w = cvt_pk_bf16(v1[2], v1[3]);
;                     *(u32x4*)(dbase + (size_t)(ai * HALF + m * 16) * 2048 + bj * HALF) = w; }
	v_cvt_pk_bf16_f32 v181, v182, v183
	v_cvt_pk_bf16_f32 v182, v190, v191
	v_cvt_pk_bf16_f32 v183, v188, v189
	global_store_dwordx4 v[186:187], v[180:183], off offset:256
	v_pk_mul_f32 v[186:187], v[58:59], v[158:159]
	v_pk_mul_f32 v[188:189], v[56:57], v[160:161]
	v_pk_mul_f32 v[182:183], v[62:63], v[162:163]
	v_pk_mul_f32 v[180:181], v[60:61], v[164:165]
	v_pk_mul_f32 v[190:191], v[24:25], v[168:169]
	v_cvt_pk_bf16_f32 v180, v180, v181
	v_cvt_pk_bf16_f32 v181, v182, v183
	v_cvt_pk_bf16_f32 v182, v188, v189
	v_cvt_pk_bf16_f32 v183, v186, v187
	v_add_co_u32_e32 v186, vcc, s4, v174
	v_pk_mul_f32 v[188:189], v[26:27], v[166:167]
	s_nop 0
	v_addc_co_u32_e32 v187, vcc, 0, v175, vcc
	global_store_dwordx4 v[186:187], v[180:183], off
	s_mov_b32 s4, 0x90000
	s_nop 0
	v_pk_mul_f32 v[182:183], v[30:31], v[170:171]
	v_pk_mul_f32 v[180:181], v[28:29], v[172:173]
	s_nop 0
	v_cvt_pk_bf16_f32 v180, v180, v181
	v_cvt_pk_bf16_f32 v181, v182, v183
	v_cvt_pk_bf16_f32 v182, v190, v191
	v_cvt_pk_bf16_f32 v183, v188, v189
	global_store_dwordx4 v[186:187], v[180:183], off offset:256
	v_pk_mul_f32 v[186:187], v[50:51], v[158:159]
	v_pk_mul_f32 v[188:189], v[48:49], v[160:161]
	v_pk_mul_f32 v[182:183], v[54:55], v[162:163]
	v_pk_mul_f32 v[180:181], v[52:53], v[164:165]
	v_pk_mul_f32 v[190:191], v[16:17], v[168:169]
	v_cvt_pk_bf16_f32 v180, v180, v181
	v_cvt_pk_bf16_f32 v181, v182, v183
	v_cvt_pk_bf16_f32 v182, v188, v189
	v_cvt_pk_bf16_f32 v183, v186, v187
	v_add_co_u32_e32 v186, vcc, s4, v174
	v_pk_mul_f32 v[188:189], v[18:19], v[166:167]
	s_nop 0
	v_addc_co_u32_e32 v187, vcc, 0, v175, vcc
	global_store_dwordx4 v[186:187], v[180:183], off
	s_mov_b32 s4, 0xa0000
	s_nop 0
	v_pk_mul_f32 v[182:183], v[22:23], v[170:171]
	v_pk_mul_f32 v[180:181], v[20:21], v[172:173]
	s_nop 0
	v_cvt_pk_bf16_f32 v180, v180, v181
	v_cvt_pk_bf16_f32 v181, v182, v183
	v_cvt_pk_bf16_f32 v182, v190, v191
	v_cvt_pk_bf16_f32 v183, v188, v189
	global_store_dwordx4 v[186:187], v[180:183], off offset:256
	v_pk_mul_f32 v[186:187], v[42:43], v[158:159]
	v_pk_mul_f32 v[188:189], v[40:41], v[160:161]
	v_pk_mul_f32 v[182:183], v[46:47], v[162:163]
	v_pk_mul_f32 v[180:181], v[44:45], v[164:165]
	v_pk_mul_f32 v[162:163], v[38:39], v[162:163]
	v_cvt_pk_bf16_f32 v180, v180, v181
	v_cvt_pk_bf16_f32 v181, v182, v183
	v_cvt_pk_bf16_f32 v182, v188, v189
	v_cvt_pk_bf16_f32 v183, v186, v187
	v_add_co_u32_e32 v186, vcc, s4, v174
	s_mov_b32 s4, 0xb0000
	s_nop 0
	v_addc_co_u32_e32 v187, vcc, 0, v175, vcc
	global_store_dwordx4 v[186:187], v[180:183], off
	v_pk_mul_f32 v[188:189], v[10:11], v[166:167]
	v_pk_mul_f32 v[190:191], v[8:9], v[168:169]
	v_pk_mul_f32 v[180:181], v[12:13], v[172:173]
	v_pk_mul_f32 v[182:183], v[14:15], v[170:171]
	v_cvt_pk_bf16_f32 v180, v180, v181
	v_pk_mul_f32 v[164:165], v[36:37], v[164:165]
	v_cvt_pk_bf16_f32 v181, v182, v183
	v_cvt_pk_bf16_f32 v182, v190, v191
	v_cvt_pk_bf16_f32 v183, v188, v189
	global_store_dwordx4 v[186:187], v[180:183], off offset:256
	v_pk_mul_f32 v[160:161], v[32:33], v[160:161]
	s_nop 0
	v_pk_mul_f32 v[180:181], v[34:35], v[158:159]
	v_cvt_pk_bf16_f32 v158, v164, v165
	v_cvt_pk_bf16_f32 v159, v162, v163
	v_add_co_u32_e32 v162, vcc, s4, v174
	v_cvt_pk_bf16_f32 v160, v160, v161
	v_cvt_pk_bf16_f32 v161, v180, v181
	v_pk_mul_f32 v[164:165], v[2:3], v[166:167]
	s_nop 0
	v_addc_co_u32_e32 v163, vcc, 0, v175, vcc
	global_store_dwordx4 v[162:163], v[158:161], off
	v_pk_mul_f32 v[166:167], v[0:1], v[168:169]
	s_nop 0
	v_pk_mul_f32 v[160:161], v[6:7], v[170:171]
	v_pk_mul_f32 v[158:159], v[4:5], v[172:173]
	s_nop 0
	v_cvt_pk_bf16_f32 v158, v158, v159
	v_cvt_pk_bf16_f32 v159, v160, v161
	v_cvt_pk_bf16_f32 v160, v166, v167
	v_cvt_pk_bf16_f32 v161, v164, v165
	global_store_dwordx4 v[162:163], v[158:161], off offset:256

;     __device__ __forceinline__ void operator()(const f32x4 (&acc)[2][2][4][2], const Unit& u, int wr, int wc, int fr, int fq) const {
;     ...
;         const float* gp = gate + (size_t)mrow * 18432 + col0;
;         f32x4 gv[2][2];
; #pragma unroll
;         for (int bj = 0; bj < 2; ++bj)
; #pragma unroll
;             for (int n = 0; n < 2; ++n) gv[bj][n] = *(const f32x4*)(gp + bj * HALF + 4 * n) * coef;
;         bf16_t* dbase = D + ((size_t)u.pm * BM + rloc0) * 2048 + col0;
.LBB0_1420:
	s_mul_i32 s4, s6, 33
	s_sub_i32 s4, s20, s4
	s_cmp_lg_u32 s4, 0
	s_cselect_b32 s4, s6, 2
	s_mul_hi_i32 s5, s4, 0x12000
	s_mul_i32 s4, s4, 0x12000
	s_add_u32 s4, s3, s4
	s_addc_u32 s5, s42, s5
	v_lshl_add_u64 v[170:171], v[174:175], 2, s[4:5]
	global_load_dwordx4 v[166:169], v[170:171], off offset:16
	global_load_dwordx4 v[158:161], v[170:171], off
	global_load_dwordx4 v[180:183], v[170:171], off offset:528
	global_load_dwordx4 v[244:247], v[170:171], off offset:512
	s_ashr_i32 s21, s20, 31
	s_lshl_b64 s[4:5], s[20:21], 20
	s_waitcnt vmcnt(2)
	v_pk_mul_f32 v[162:163], v[160:161], 0.5 op_sel_hi:[1,0]
	v_pk_mul_f32 v[164:165], v[158:159], 0.5 op_sel_hi:[1,0]
	v_pk_mul_f32 v[158:159], v[168:169], 0.5 op_sel_hi:[1,0]
	v_pk_mul_f32 v[160:161], v[166:167], 0.5 op_sel_hi:[1,0]


; __device__ __forceinline__ unsigned cvt_pk_bf16(float lo, float hi) { unsigned r; asm volatile("v_cvt_pk_bf16_f32 %0, %1, %2" : "=v"(r) : "v"(lo), "v"(hi)); return r; }
;     __device__ __forceinline__ void operator()(const f32x4 (&acc)[2][2][4][2], const Unit& u, int wr, int wc, int fr, int fq) const {
;     ...
;             for (int n = 0; n < 2; ++n) gv[bj][n] = *(const f32x4*)(gp + bj * HALF + 4 * n) * coef;
;         bf16_t* dbase = D + ((size_t)u.pm * BM + rloc0) * 2048 + col0;
; #pragma unroll
;         for (int ai = 0; ai < 2; ++ai)
; #pragma unroll
;             for (int m = 0; m < 4; ++m)
; #pragma unroll
;                 for (int bj = 0; bj < 2; ++bj) { const f32x4 v0 = gv[bj][0] * acc[ai][bj][m][0], v1 = gv[bj][1] * acc[ai][bj][m][1];
;                     u32x4 w; w.x = cvt_pk_bf16(v0[0], v0[1]); w.y = cvt_pk_bf16(v0[2], v0[3]); w.z = cvt_pk_bf16(v1[0], v1[1]); w.w = cvt_pk_bf16(v1[2], v1[3]);
;                     *(u32x4*)(dbase + (size_t)(ai * HALF + m * 16) * 2048 + bj * HALF) = w; }
	v_pk_mul_f32 v[190:191], v[122:123], v[158:159]
	v_pk_mul_f32 v[192:193], v[120:121], v[160:161]
	s_waitcnt vmcnt(0)
	v_pk_mul_f32 v[170:171], v[246:247], 0.5 op_sel_hi:[1,0]
	v_pk_mul_f32 v[168:169], v[180:181], 0.5 op_sel_hi:[1,0]
	v_lshl_add_u64 v[180:181], v[152:153], 0, s[4:5]
	v_pk_mul_f32 v[172:173], v[244:245], 0.5 op_sel_hi:[1,0]
	v_pk_mul_f32 v[166:167], v[182:183], 0.5 op_sel_hi:[1,0]
	v_lshl_add_u64 v[174:175], v[174:175], 1, v[180:181]
	v_pk_mul_f32 v[182:183], v[126:127], v[162:163]
	v_pk_mul_f32 v[180:181], v[124:125], v[164:165]
	s_mov_b32 s4, 0x10000
	v_cvt_pk_bf16_f32 v180, v180, v181
	v_cvt_pk_bf16_f32 v181, v182, v183
	v_cvt_pk_bf16_f32 v182, v192, v193
	v_cvt_pk_bf16_f32 v183, v190, v191
	global_store_dwordx4 v[174:175], v[180:183], off
	v_pk_mul_f32 v[190:191], v[90:91], v[166:167]
	v_pk_mul_f32 v[192:193], v[88:89], v[168:169]
	v_pk_mul_f32 v[182:183], v[94:95], v[170:171]
	v_pk_mul_f32 v[180:181], v[92:93], v[172:173]
	v_pk_mul_f32 v[194:195], v[80:81], v[168:169]
	v_cvt_pk_bf16_f32 v180, v180, v181
	v_cvt_pk_bf16_f32 v181, v182, v183
	v_cvt_pk_bf16_f32 v182, v192, v193
	v_cvt_pk_bf16_f32 v183, v190, v191
	global_store_dwordx4 v[174:175], v[180:183], off offset:256
	v_pk_mul_f32 v[190:191], v[114:115], v[158:159]
	v_pk_mul_f32 v[192:193], v[112:113], v[160:161]
	v_pk_mul_f32 v[182:183], v[118:119], v[162:163]
	v_pk_mul_f32 v[180:181], v[116:117], v[164:165]
	s_nop 0
	v_cvt_pk_bf16_f32 v180, v180, v181
	v_cvt_pk_bf16_f32 v181, v182, v183
	v_cvt_pk_bf16_f32 v182, v192, v193
	v_cvt_pk_bf16_f32 v183, v190, v191
	v_add_co_u32_e32 v190, vcc, s4, v174
	v_pk_mul_f32 v[192:193], v[82:83], v[166:167]
	s_nop 0
	v_addc_co_u32_e32 v191, vcc, 0, v175, vcc
	global_store_dwordx4 v[190:191], v[180:183], off
	s_mov_b32 s4, 0x20000
	s_nop 0
	v_pk_mul_f32 v[182:183], v[86:87], v[170:171]
	v_pk_mul_f32 v[180:181], v[84:85], v[172:173]
	s_nop 0
	v_cvt_pk_bf16_f32 v180, v180, v181
	v_cvt_pk_bf16_f32 v181, v182, v183
	v_cvt_pk_bf16_f32 v182, v194, v195
	v_cvt_pk_bf16_f32 v183, v192, v193
	global_store_dwordx4 v[190:191], v[180:183], off offset:256
	v_pk_mul_f32 v[190:191], v[106:107], v[158:159]
	v_pk_mul_f32 v[192:193], v[104:105], v[160:161]
	v_pk_mul_f32 v[182:183], v[110:111], v[162:163]
	v_pk_mul_f32 v[180:181], v[108:109], v[164:165]
	v_pk_mul_f32 v[194:195], v[72:73], v[168:169]
	v_cvt_pk_bf16_f32 v180, v180, v181
	v_cvt_pk_bf16_f32 v181, v182, v183
	v_cvt_pk_bf16_f32 v182, v192, v193
	v_cvt_pk_bf16_f32 v183, v190, v191
	v_add_co_u32_e32 v190, vcc, s4, v174
	v_pk_mul_f32 v[192:193], v[74:75], v[166:167]
	s_nop 0
	v_addc_co_u32_e32 v191, vcc, 0, v175, vcc
	global_store_dwordx4 v[190:191], v[180:183], off
	s_mov_b32 s4, 0x30000
	s_nop 0
	v_pk_mul_f32 v[182:183], v[78:79], v[170:171]
	v_pk_mul_f32 v[180:181], v[76:77], v[172:173]
	s_nop 0
	v_cvt_pk_bf16_f32 v180, v180, v181
	v_cvt_pk_bf16_f32 v181, v182, v183
	v_cvt_pk_bf16_f32 v182, v194, v195
	v_cvt_pk_bf16_f32 v183, v192, v193
	global_store_dwordx4 v[190:191], v[180:183], off offset:256
	v_pk_mul_f32 v[190:191], v[98:99], v[158:159]
	v_pk_mul_f32 v[192:193], v[96:97], v[160:161]
	v_pk_mul_f32 v[182:183], v[102:103], v[162:163]
	v_pk_mul_f32 v[180:181], v[100:101], v[164:165]
	v_pk_mul_f32 v[194:195], v[64:65], v[168:169]
	v_cvt_pk_bf16_f32 v180, v180, v181
	v_cvt_pk_bf16_f32 v181, v182, v183
	v_cvt_pk_bf16_f32 v182, v192, v193
	v_cvt_pk_bf16_f32 v183, v190, v191
	v_add_co_u32_e32 v190, vcc, s4, v174
	v_pk_mul_f32 v[192:193], v[66:67], v[166:167]
	s_nop 0
	v_addc_co_u32_e32 v191, vcc, 0, v175, vcc
	global_store_dwordx4 v[190:191], v[180:183], off
	s_mov_b32 s4, 0x80000
	s_nop 0
	v_pk_mul_f32 v[182:183], v[70:71], v[170:171]
	v_pk_mul_f32 v[180:181], v[68:69], v[172:173]
	s_nop 0
	v_cvt_pk_bf16_f32 v180, v180, v181
; __device__ __forceinline__ unsigned cvt_pk_bf16(float lo, float hi) { unsigned r; asm volatile("v_cvt_pk_bf16_f32 %0, %1, %2" : "=v"(r) : "v"(lo), "v"(hi)); return r; }
;     __device__ __forceinline__ void operator()(const f32x4 (&acc)[2][2][4][2], const Unit& u, int wr, int wc, int fr, int fq) const {
;     ...
; #pragma unroll
;         for (int ai = 0; ai < 2; ++ai)
; #pragma unroll
;             for (int m = 0; m < 4; ++m)
; #pragma unroll
;                 for (int bj = 0; bj < 2; ++bj) { const f32x4 v0 = gv[bj][0] * acc[ai][bj][m][0], v1 = gv[bj][1] * acc[ai][bj][m][1];
;                     u32x4 w; w.x = cvt_pk_bf16(v0[0], v0[1]); w.y = cvt_pk_bf16(v0[2], v0[3]); w.z = cvt_pk_bf16(v1[0], v1[1]); w.w = cvt_pk_bf16(v1[2], v1[3]);
;                     *(u32x4*)(dbase + (size_t)(ai * HALF + m * 16) * 2048 + bj * HALF) = w; }
	v_cvt_pk_bf16_f32 v181, v182, v183
	v_cvt_pk_bf16_f32 v182, v194, v195
	v_cvt_pk_bf16_f32 v183, v192, v193
	global_store_dwordx4 v[190:191], v[180:183], off offset:256
	v_pk_mul_f32 v[190:191], v[58:59], v[158:159]
	v_pk_mul_f32 v[192:193], v[56:57], v[160:161]
	v_pk_mul_f32 v[182:183], v[62:63], v[162:163]
	v_pk_mul_f32 v[180:181], v[60:61], v[164:165]
	v_pk_mul_f32 v[194:195], v[24:25], v[168:169]
	v_cvt_pk_bf16_f32 v180, v180, v181
	v_cvt_pk_bf16_f32 v181, v182, v183
	v_cvt_pk_bf16_f32 v182, v192, v193
	v_cvt_pk_bf16_f32 v183, v190, v191
	v_add_co_u32_e32 v190, vcc, s4, v174
	v_pk_mul_f32 v[192:193], v[26:27], v[166:167]
	s_nop 0
	v_addc_co_u32_e32 v191, vcc, 0, v175, vcc
	global_store_dwordx4 v[190:191], v[180:183], off
	s_mov_b32 s4, 0x90000
	s_nop 0
	v_pk_mul_f32 v[182:183], v[30:31], v[170:171]
	v_pk_mul_f32 v[180:181], v[28:29], v[172:173]
	s_nop 0
	v_cvt_pk_bf16_f32 v180, v180, v181
	v_cvt_pk_bf16_f32 v181, v182, v183
	v_cvt_pk_bf16_f32 v182, v194, v195
	v_cvt_pk_bf16_f32 v183, v192, v193
	global_store_dwordx4 v[190:191], v[180:183], off offset:256
	v_pk_mul_f32 v[190:191], v[50:51], v[158:159]
	v_pk_mul_f32 v[192:193], v[48:49], v[160:161]
	v_pk_mul_f32 v[182:183], v[54:55], v[162:163]
	v_pk_mul_f32 v[180:181], v[52:53], v[164:165]
	v_pk_mul_f32 v[194:195], v[16:17], v[168:169]
	v_cvt_pk_bf16_f32 v180, v180, v181
	v_cvt_pk_bf16_f32 v181, v182, v183
	v_cvt_pk_bf16_f32 v182, v192, v193
	v_cvt_pk_bf16_f32 v183, v190, v191
	v_add_co_u32_e32 v190, vcc, s4, v174
	v_pk_mul_f32 v[192:193], v[18:19], v[166:167]
	s_nop 0
	v_addc_co_u32_e32 v191, vcc, 0, v175, vcc
	global_store_dwordx4 v[190:191], v[180:183], off
	s_mov_b32 s4, 0xa0000
	s_nop 0
	v_pk_mul_f32 v[182:183], v[22:23], v[170:171]
	v_pk_mul_f32 v[180:181], v[20:21], v[172:173]
	s_nop 0
	v_cvt_pk_bf16_f32 v180, v180, v181
	v_cvt_pk_bf16_f32 v181, v182, v183
	v_cvt_pk_bf16_f32 v182, v194, v195
	v_cvt_pk_bf16_f32 v183, v192, v193
	global_store_dwordx4 v[190:191], v[180:183], off offset:256
	v_pk_mul_f32 v[190:191], v[42:43], v[158:159]
	v_pk_mul_f32 v[192:193], v[40:41], v[160:161]
	v_pk_mul_f32 v[182:183], v[46:47], v[162:163]
	v_pk_mul_f32 v[180:181], v[44:45], v[164:165]
	v_pk_mul_f32 v[162:163], v[38:39], v[162:163]
	v_cvt_pk_bf16_f32 v180, v180, v181
	v_cvt_pk_bf16_f32 v181, v182, v183
	v_cvt_pk_bf16_f32 v182, v192, v193
	v_cvt_pk_bf16_f32 v183, v190, v191
	v_add_co_u32_e32 v190, vcc, s4, v174
	s_mov_b32 s4, 0xb0000
	s_nop 0
	v_addc_co_u32_e32 v191, vcc, 0, v175, vcc
	global_store_dwordx4 v[190:191], v[180:183], off
	v_pk_mul_f32 v[192:193], v[10:11], v[166:167]
	v_pk_mul_f32 v[194:195], v[8:9], v[168:169]
	v_pk_mul_f32 v[180:181], v[12:13], v[172:173]
	v_pk_mul_f32 v[182:183], v[14:15], v[170:171]
	v_cvt_pk_bf16_f32 v180, v180, v181
	v_pk_mul_f32 v[164:165], v[36:37], v[164:165]
	v_cvt_pk_bf16_f32 v181, v182, v183
	v_cvt_pk_bf16_f32 v182, v194, v195
	v_cvt_pk_bf16_f32 v183, v192, v193
	global_store_dwordx4 v[190:191], v[180:183], off offset:256
	v_pk_mul_f32 v[160:161], v[32:33], v[160:161]
	s_nop 0
	v_pk_mul_f32 v[180:181], v[34:35], v[158:159]
	v_cvt_pk_bf16_f32 v158, v164, v165
	v_cvt_pk_bf16_f32 v159, v162, v163
	v_add_co_u32_e32 v162, vcc, s4, v174
	v_cvt_pk_bf16_f32 v160, v160, v161
	v_cvt_pk_bf16_f32 v161, v180, v181
	v_pk_mul_f32 v[164:165], v[2:3], v[166:167]
	s_nop 0
	v_addc_co_u32_e32 v163, vcc, 0, v175, vcc
	global_store_dwordx4 v[162:163], v[158:161], off
	v_pk_mul_f32 v[166:167], v[0:1], v[168:169]
	s_nop 0
	v_pk_mul_f32 v[160:161], v[6:7], v[170:171]
	v_pk_mul_f32 v[158:159], v[4:5], v[172:173]
	s_nop 0
	v_cvt_pk_bf16_f32 v158, v158, v159
	v_cvt_pk_bf16_f32 v159, v160, v161
	v_cvt_pk_bf16_f32 v160, v166, v167
	v_cvt_pk_bf16_f32 v161, v164, v165
	global_store_dwordx4 v[162:163], v[158:161], off offset:256

;     __device__ __forceinline__ void operator()(const f32x4 (&acc)[2][2][4][2], const Unit& u, int wr, int wc, int fr, int fq) const {
;     ...
;         const float* gp = gate + (size_t)mrow * 18432 + col0;
;         f32x4 gv[2][2];
; #pragma unroll
;         for (int bj = 0; bj < 2; ++bj)
; #pragma unroll
;             for (int n = 0; n < 2; ++n) gv[bj][n] = *(const f32x4*)(gp + bj * HALF + 4 * n) * coef;
;         bf16_t* dbase = D + ((size_t)u.pm * BM + rloc0) * 2048 + col0;
.LBB0_1770:
	s_mul_i32 s4, s6, 33
	s_sub_i32 s4, s20, s4
	s_cmp_lg_u32 s4, 0
	s_cselect_b32 s4, s6, 2
	s_mul_hi_i32 s5, s4, 0x12000
	s_mul_i32 s4, s4, 0x12000
	s_add_u32 s4, s3, s4
	s_addc_u32 s5, s94, s5
	v_lshl_add_u64 v[170:171], v[174:175], 2, s[4:5]
	global_load_dwordx4 v[166:169], v[170:171], off offset:16
	global_load_dwordx4 v[158:161], v[170:171], off
	global_load_dwordx4 v[180:183], v[170:171], off offset:528
	global_load_dwordx4 v[244:247], v[170:171], off offset:512
	s_ashr_i32 s21, s20, 31
	s_lshl_b64 s[4:5], s[20:21], 20
	s_waitcnt vmcnt(2)
	v_pk_mul_f32 v[162:163], v[160:161], 0.5 op_sel_hi:[1,0]
	v_pk_mul_f32 v[164:165], v[158:159], 0.5 op_sel_hi:[1,0]
	v_pk_mul_f32 v[158:159], v[168:169], 0.5 op_sel_hi:[1,0]
	v_pk_mul_f32 v[160:161], v[166:167], 0.5 op_sel_hi:[1,0]


; __device__ __forceinline__ unsigned cvt_pk_bf16(float lo, float hi) { unsigned r; asm volatile("v_cvt_pk_bf16_f32 %0, %1, %2" : "=v"(r) : "v"(lo), "v"(hi)); return r; }
;     __device__ __forceinline__ void operator()(const f32x4 (&acc)[2][2][4][2], const Unit& u, int wr, int wc, int fr, int fq) const {
;     ...
;             for (int n = 0; n < 2; ++n) gv[bj][n] = *(const f32x4*)(gp + bj * HALF + 4 * n) * coef;
;         bf16_t* dbase = D + ((size_t)u.pm * BM + rloc0) * 2048 + col0;
; #pragma unroll
;         for (int ai = 0; ai < 2; ++ai)
; #pragma unroll
;             for (int m = 0; m < 4; ++m)
; #pragma unroll
;                 for (int bj = 0; bj < 2; ++bj) { const f32x4 v0 = gv[bj][0] * acc[ai][bj][m][0], v1 = gv[bj][1] * acc[ai][bj][m][1];
;                     u32x4 w; w.x = cvt_pk_bf16(v0[0], v0[1]); w.y = cvt_pk_bf16(v0[2], v0[3]); w.z = cvt_pk_bf16(v1[0], v1[1]); w.w = cvt_pk_bf16(v1[2], v1[3]);
;                     *(u32x4*)(dbase + (size_t)(ai * HALF + m * 16) * 2048 + bj * HALF) = w; }
	v_pk_mul_f32 v[190:191], v[122:123], v[158:159]
	v_pk_mul_f32 v[192:193], v[120:121], v[160:161]
	s_waitcnt vmcnt(0)
	v_pk_mul_f32 v[170:171], v[246:247], 0.5 op_sel_hi:[1,0]
	v_pk_mul_f32 v[168:169], v[180:181], 0.5 op_sel_hi:[1,0]
	v_lshl_add_u64 v[180:181], v[152:153], 0, s[4:5]
	v_pk_mul_f32 v[172:173], v[244:245], 0.5 op_sel_hi:[1,0]
	v_pk_mul_f32 v[166:167], v[182:183], 0.5 op_sel_hi:[1,0]
	v_lshl_add_u64 v[174:175], v[174:175], 1, v[180:181]
	v_pk_mul_f32 v[182:183], v[126:127], v[162:163]
	v_pk_mul_f32 v[180:181], v[124:125], v[164:165]
	s_mov_b32 s4, 0x10000
	v_cvt_pk_bf16_f32 v180, v180, v181
	v_cvt_pk_bf16_f32 v181, v182, v183
	v_cvt_pk_bf16_f32 v182, v192, v193
	v_cvt_pk_bf16_f32 v183, v190, v191
	global_store_dwordx4 v[174:175], v[180:183], off
	v_pk_mul_f32 v[190:191], v[90:91], v[166:167]
	v_pk_mul_f32 v[192:193], v[88:89], v[168:169]
	v_pk_mul_f32 v[182:183], v[94:95], v[170:171]
	v_pk_mul_f32 v[180:181], v[92:93], v[172:173]
	v_pk_mul_f32 v[194:195], v[80:81], v[168:169]
	v_cvt_pk_bf16_f32 v180, v180, v181
	v_cvt_pk_bf16_f32 v181, v182, v183
	v_cvt_pk_bf16_f32 v182, v192, v193
	v_cvt_pk_bf16_f32 v183, v190, v191
	global_store_dwordx4 v[174:175], v[180:183], off offset:256
	v_pk_mul_f32 v[190:191], v[114:115], v[158:159]
	v_pk_mul_f32 v[192:193], v[112:113], v[160:161]
	v_pk_mul_f32 v[182:183], v[118:119], v[162:163]
	v_pk_mul_f32 v[180:181], v[116:117], v[164:165]
	s_nop 0
	v_cvt_pk_bf16_f32 v180, v180, v181
	v_cvt_pk_bf16_f32 v181, v182, v183
	v_cvt_pk_bf16_f32 v182, v192, v193
	v_cvt_pk_bf16_f32 v183, v190, v191
	v_add_co_u32_e32 v190, vcc, s4, v174
	v_pk_mul_f32 v[192:193], v[82:83], v[166:167]
	s_nop 0
	v_addc_co_u32_e32 v191, vcc, 0, v175, vcc
	global_store_dwordx4 v[190:191], v[180:183], off
	s_mov_b32 s4, 0x20000
	s_nop 0
	v_pk_mul_f32 v[182:183], v[86:87], v[170:171]
	v_pk_mul_f32 v[180:181], v[84:85], v[172:173]
	s_nop 0
	v_cvt_pk_bf16_f32 v180, v180, v181
	v_cvt_pk_bf16_f32 v181, v182, v183
	v_cvt_pk_bf16_f32 v182, v194, v195
	v_cvt_pk_bf16_f32 v183, v192, v193
	global_store_dwordx4 v[190:191], v[180:183], off offset:256
	v_pk_mul_f32 v[190:191], v[106:107], v[158:159]
	v_pk_mul_f32 v[192:193], v[104:105], v[160:161]
	v_pk_mul_f32 v[182:183], v[110:111], v[162:163]
	v_pk_mul_f32 v[180:181], v[108:109], v[164:165]
	v_pk_mul_f32 v[194:195], v[72:73], v[168:169]
	v_cvt_pk_bf16_f32 v180, v180, v181
	v_cvt_pk_bf16_f32 v181, v182, v183
	v_cvt_pk_bf16_f32 v182, v192, v193
	v_cvt_pk_bf16_f32 v183, v190, v191
	v_add_co_u32_e32 v190, vcc, s4, v174
	v_pk_mul_f32 v[192:193], v[74:75], v[166:167]
	s_nop 0
	v_addc_co_u32_e32 v191, vcc, 0, v175, vcc
	global_store_dwordx4 v[190:191], v[180:183], off
	s_mov_b32 s4, 0x30000
	s_nop 0
	v_pk_mul_f32 v[182:183], v[78:79], v[170:171]
	v_pk_mul_f32 v[180:181], v[76:77], v[172:173]
	s_nop 0
	v_cvt_pk_bf16_f32 v180, v180, v181
	v_cvt_pk_bf16_f32 v181, v182, v183
	v_cvt_pk_bf16_f32 v182, v194, v195
	v_cvt_pk_bf16_f32 v183, v192, v193
	global_store_dwordx4 v[190:191], v[180:183], off offset:256
	v_pk_mul_f32 v[190:191], v[98:99], v[158:159]
	v_pk_mul_f32 v[192:193], v[96:97], v[160:161]
	v_pk_mul_f32 v[182:183], v[102:103], v[162:163]
	v_pk_mul_f32 v[180:181], v[100:101], v[164:165]
	v_pk_mul_f32 v[194:195], v[64:65], v[168:169]
	v_cvt_pk_bf16_f32 v180, v180, v181
	v_cvt_pk_bf16_f32 v181, v182, v183
	v_cvt_pk_bf16_f32 v182, v192, v193
	v_cvt_pk_bf16_f32 v183, v190, v191
	v_add_co_u32_e32 v190, vcc, s4, v174
	v_pk_mul_f32 v[192:193], v[66:67], v[166:167]
	s_nop 0
	v_addc_co_u32_e32 v191, vcc, 0, v175, vcc
	global_store_dwordx4 v[190:191], v[180:183], off
	s_mov_b32 s4, 0x80000
	s_nop 0
	v_pk_mul_f32 v[182:183], v[70:71], v[170:171]
	v_pk_mul_f32 v[180:181], v[68:69], v[172:173]
	s_nop 0
	v_cvt_pk_bf16_f32 v180, v180, v181
; __device__ __forceinline__ unsigned cvt_pk_bf16(float lo, float hi) { unsigned r; asm volatile("v_cvt_pk_bf16_f32 %0, %1, %2" : "=v"(r) : "v"(lo), "v"(hi)); return r; }
;     __device__ __forceinline__ void operator()(const f32x4 (&acc)[2][2][4][2], const Unit& u, int wr, int wc, int fr, int fq) const {
;     ...
; #pragma unroll
;         for (int ai = 0; ai < 2; ++ai)
; #pragma unroll
;             for (int m = 0; m < 4; ++m)
; #pragma unroll
;                 for (int bj = 0; bj < 2; ++bj) { const f32x4 v0 = gv[bj][0] * acc[ai][bj][m][0], v1 = gv[bj][1] * acc[ai][bj][m][1];
;                     u32x4 w; w.x = cvt_pk_bf16(v0[0], v0[1]); w.y = cvt_pk_bf16(v0[2], v0[3]); w.z = cvt_pk_bf16(v1[0], v1[1]); w.w = cvt_pk_bf16(v1[2], v1[3]);
;                     *(u32x4*)(dbase + (size_t)(ai * HALF + m * 16) * 2048 + bj * HALF) = w; }
	v_cvt_pk_bf16_f32 v181, v182, v183
	v_cvt_pk_bf16_f32 v182, v194, v195
	v_cvt_pk_bf16_f32 v183, v192, v193
	global_store_dwordx4 v[190:191], v[180:183], off offset:256
	v_pk_mul_f32 v[190:191], v[58:59], v[158:159]
	v_pk_mul_f32 v[192:193], v[56:57], v[160:161]
	v_pk_mul_f32 v[182:183], v[62:63], v[162:163]
	v_pk_mul_f32 v[180:181], v[60:61], v[164:165]
	v_pk_mul_f32 v[194:195], v[24:25], v[168:169]
	v_cvt_pk_bf16_f32 v180, v180, v181
	v_cvt_pk_bf16_f32 v181, v182, v183
	v_cvt_pk_bf16_f32 v182, v192, v193
	v_cvt_pk_bf16_f32 v183, v190, v191
	v_add_co_u32_e32 v190, vcc, s4, v174
	v_pk_mul_f32 v[192:193], v[26:27], v[166:167]
	s_nop 0
	v_addc_co_u32_e32 v191, vcc, 0, v175, vcc
	global_store_dwordx4 v[190:191], v[180:183], off
	s_mov_b32 s4, 0x90000
	s_nop 0
	v_pk_mul_f32 v[182:183], v[30:31], v[170:171]
	v_pk_mul_f32 v[180:181], v[28:29], v[172:173]
	s_nop 0
	v_cvt_pk_bf16_f32 v180, v180, v181
	v_cvt_pk_bf16_f32 v181, v182, v183
	v_cvt_pk_bf16_f32 v182, v194, v195
	v_cvt_pk_bf16_f32 v183, v192, v193
	global_store_dwordx4 v[190:191], v[180:183], off offset:256
	v_pk_mul_f32 v[190:191], v[50:51], v[158:159]
	v_pk_mul_f32 v[192:193], v[48:49], v[160:161]
	v_pk_mul_f32 v[182:183], v[54:55], v[162:163]
	v_pk_mul_f32 v[180:181], v[52:53], v[164:165]
	v_pk_mul_f32 v[194:195], v[16:17], v[168:169]
	v_cvt_pk_bf16_f32 v180, v180, v181
	v_cvt_pk_bf16_f32 v181, v182, v183
	v_cvt_pk_bf16_f32 v182, v192, v193
	v_cvt_pk_bf16_f32 v183, v190, v191
	v_add_co_u32_e32 v190, vcc, s4, v174
	v_pk_mul_f32 v[192:193], v[18:19], v[166:167]
	s_nop 0
	v_addc_co_u32_e32 v191, vcc, 0, v175, vcc
	global_store_dwordx4 v[190:191], v[180:183], off
	s_mov_b32 s4, 0xa0000
	s_nop 0
	v_pk_mul_f32 v[182:183], v[22:23], v[170:171]
	v_pk_mul_f32 v[180:181], v[20:21], v[172:173]
	s_nop 0
	v_cvt_pk_bf16_f32 v180, v180, v181
	v_cvt_pk_bf16_f32 v181, v182, v183
	v_cvt_pk_bf16_f32 v182, v194, v195
	v_cvt_pk_bf16_f32 v183, v192, v193
	global_store_dwordx4 v[190:191], v[180:183], off offset:256
	v_pk_mul_f32 v[190:191], v[42:43], v[158:159]
	v_pk_mul_f32 v[192:193], v[40:41], v[160:161]
	v_pk_mul_f32 v[182:183], v[46:47], v[162:163]
	v_pk_mul_f32 v[180:181], v[44:45], v[164:165]
	v_pk_mul_f32 v[162:163], v[38:39], v[162:163]
	v_cvt_pk_bf16_f32 v180, v180, v181
	v_cvt_pk_bf16_f32 v181, v182, v183
	v_cvt_pk_bf16_f32 v182, v192, v193
	v_cvt_pk_bf16_f32 v183, v190, v191
	v_add_co_u32_e32 v190, vcc, s4, v174
	s_mov_b32 s4, 0xb0000
	s_nop 0
	v_addc_co_u32_e32 v191, vcc, 0, v175, vcc
	global_store_dwordx4 v[190:191], v[180:183], off
	v_pk_mul_f32 v[192:193], v[10:11], v[166:167]
	v_pk_mul_f32 v[194:195], v[8:9], v[168:169]
	v_pk_mul_f32 v[180:181], v[12:13], v[172:173]
	v_pk_mul_f32 v[182:183], v[14:15], v[170:171]
	v_cvt_pk_bf16_f32 v180, v180, v181
	v_pk_mul_f32 v[164:165], v[36:37], v[164:165]
	v_cvt_pk_bf16_f32 v181, v182, v183
	v_cvt_pk_bf16_f32 v182, v194, v195
	v_cvt_pk_bf16_f32 v183, v192, v193
	global_store_dwordx4 v[190:191], v[180:183], off offset:256
	v_pk_mul_f32 v[160:161], v[32:33], v[160:161]
	s_nop 0
	v_pk_mul_f32 v[180:181], v[34:35], v[158:159]
	v_cvt_pk_bf16_f32 v158, v164, v165
	v_cvt_pk_bf16_f32 v159, v162, v163
	v_add_co_u32_e32 v162, vcc, s4, v174
	v_cvt_pk_bf16_f32 v160, v160, v161
	v_cvt_pk_bf16_f32 v161, v180, v181
	v_pk_mul_f32 v[164:165], v[2:3], v[166:167]
	s_nop 0
	v_addc_co_u32_e32 v163, vcc, 0, v175, vcc
	global_store_dwordx4 v[162:163], v[158:161], off
	v_pk_mul_f32 v[166:167], v[0:1], v[168:169]
	s_nop 0
	v_pk_mul_f32 v[160:161], v[6:7], v[170:171]
	v_pk_mul_f32 v[158:159], v[4:5], v[172:173]
	s_nop 0
	v_cvt_pk_bf16_f32 v158, v158, v159
	v_cvt_pk_bf16_f32 v159, v160, v161
	v_cvt_pk_bf16_f32 v160, v166, v167
	v_cvt_pk_bf16_f32 v161, v164, v165
	global_store_dwordx4 v[162:163], v[158:161], off offset:256

;     __device__ __forceinline__ void operator()(const f32x4 (&acc)[2][2][4][2], const Unit& u, int wr, int wc, int fr, int fq) const {
;     ...
;         const float* gp = gate + (size_t)mrow * 18432 + col0;
;         f32x4 gv[2][2];
; #pragma unroll
;         for (int bj = 0; bj < 2; ++bj)
; #pragma unroll
;             for (int n = 0; n < 2; ++n) gv[bj][n] = *(const f32x4*)(gp + bj * HALF + 4 * n) * coef;
;         bf16_t* dbase = D + ((size_t)u.pm * BM + rloc0) * 2048 + col0;
.LBB0_3152:
	s_mul_i32 s4, s1, 33
	s_sub_i32 s4, s16, s4
	s_cmp_lg_u32 s4, 0
	s_cselect_b32 s1, s1, 2
	s_mul_hi_i32 s5, s1, 0x12000
	s_mul_i32 s1, s1, 0x12000
	s_add_u32 s4, s60, s1
	s_addc_u32 s5, s61, s5
	v_lshl_add_u64 v[172:173], v[176:177], 2, s[4:5]
	global_load_dwordx4 v[168:171], v[172:173], off offset:16
	global_load_dwordx4 v[160:163], v[172:173], off
	global_load_dwordx4 v[190:193], v[172:173], off offset:528
	global_load_dwordx4 v[244:247], v[172:173], off offset:512
	s_ashr_i32 s17, s16, 31
	s_lshl_b64 s[4:5], s[16:17], 20
	v_lshl_add_u64 v[182:183], v[152:153], 0, s[4:5]
	v_lshl_add_u64 v[176:177], v[176:177], 1, v[182:183]
	s_mov_b32 s1, 0x10000
	s_waitcnt vmcnt(2)
	v_pk_mul_f32 v[164:165], v[162:163], 0.5 op_sel_hi:[1,0]
	v_pk_mul_f32 v[166:167], v[160:161], 0.5 op_sel_hi:[1,0]
	v_pk_mul_f32 v[160:161], v[170:171], 0.5 op_sel_hi:[1,0]
	v_pk_mul_f32 v[162:163], v[168:169], 0.5 op_sel_hi:[1,0]


; __device__ __forceinline__ unsigned cvt_pk_bf16(float lo, float hi) { unsigned r; asm volatile("v_cvt_pk_bf16_f32 %0, %1, %2" : "=v"(r) : "v"(lo), "v"(hi)); return r; }
;     __device__ __forceinline__ void operator()(const f32x4 (&acc)[2][2][4][2], const Unit& u, int wr, int wc, int fr, int fq) const {
;     ...
;             for (int n = 0; n < 2; ++n) gv[bj][n] = *(const f32x4*)(gp + bj * HALF + 4 * n) * coef;
;         bf16_t* dbase = D + ((size_t)u.pm * BM + rloc0) * 2048 + col0;
; #pragma unroll
;         for (int ai = 0; ai < 2; ++ai)
; #pragma unroll
;             for (int m = 0; m < 4; ++m)
; #pragma unroll
;                 for (int bj = 0; bj < 2; ++bj) { const f32x4 v0 = gv[bj][0] * acc[ai][bj][m][0], v1 = gv[bj][1] * acc[ai][bj][m][1];
;                     u32x4 w; w.x = cvt_pk_bf16(v0[0], v0[1]); w.y = cvt_pk_bf16(v0[2], v0[3]); w.z = cvt_pk_bf16(v1[0], v1[1]); w.w = cvt_pk_bf16(v1[2], v1[3]);
;                     *(u32x4*)(dbase + (size_t)(ai * HALF + m * 16) * 2048 + bj * HALF) = w; }
	v_pk_mul_f32 v[182:183], v[126:127], v[164:165]
	v_pk_mul_f32 v[194:195], v[122:123], v[160:161]
	s_waitcnt vmcnt(0)
	v_pk_mul_f32 v[172:173], v[246:247], 0.5 op_sel_hi:[1,0]
	v_pk_mul_f32 v[170:171], v[190:191], 0.5 op_sel_hi:[1,0]
	v_pk_mul_f32 v[190:191], v[124:125], v[166:167]
	v_pk_mul_f32 v[174:175], v[244:245], 0.5 op_sel_hi:[1,0]
	v_pk_mul_f32 v[168:169], v[192:193], 0.5 op_sel_hi:[1,0]
	v_pk_mul_f32 v[192:193], v[120:121], v[162:163]
	v_cvt_pk_bf16_f32 v190, v190, v191
	v_cvt_pk_bf16_f32 v191, v182, v183
	v_pk_mul_f32 v[182:183], v[94:95], v[172:173]
	v_cvt_pk_bf16_f32 v192, v192, v193
	v_cvt_pk_bf16_f32 v193, v194, v195
	global_store_dwordx4 v[176:177], v[190:193], off
	v_pk_mul_f32 v[194:195], v[90:91], v[168:169]
	v_pk_mul_f32 v[196:197], v[80:81], v[170:171]
	v_pk_mul_f32 v[190:191], v[92:93], v[174:175]
	v_pk_mul_f32 v[192:193], v[88:89], v[170:171]
	v_cvt_pk_bf16_f32 v190, v190, v191
	v_cvt_pk_bf16_f32 v191, v182, v183
	v_pk_mul_f32 v[182:183], v[118:119], v[164:165]
	v_cvt_pk_bf16_f32 v192, v192, v193
	v_cvt_pk_bf16_f32 v193, v194, v195
	global_store_dwordx4 v[176:177], v[190:193], off offset:256
	v_pk_mul_f32 v[194:195], v[114:115], v[160:161]
	s_nop 0
	v_pk_mul_f32 v[190:191], v[116:117], v[166:167]
	v_pk_mul_f32 v[192:193], v[112:113], v[162:163]
	v_cvt_pk_bf16_f32 v190, v190, v191
	v_cvt_pk_bf16_f32 v191, v182, v183
	v_add_co_u32_e32 v182, vcc, s1, v176
	v_cvt_pk_bf16_f32 v192, v192, v193
	v_cvt_pk_bf16_f32 v193, v194, v195
	v_pk_mul_f32 v[194:195], v[82:83], v[168:169]
	s_nop 0
	v_addc_co_u32_e32 v183, vcc, 0, v177, vcc
	global_store_dwordx4 v[182:183], v[190:193], off
	s_mov_b32 s1, 0x20000
	s_nop 0
	v_pk_mul_f32 v[190:191], v[84:85], v[174:175]
	v_pk_mul_f32 v[192:193], v[86:87], v[172:173]
	v_cvt_pk_bf16_f32 v190, v190, v191
	s_nop 0
	v_cvt_pk_bf16_f32 v191, v192, v193
	v_cvt_pk_bf16_f32 v192, v196, v197
	v_cvt_pk_bf16_f32 v193, v194, v195
	global_store_dwordx4 v[182:183], v[190:193], off offset:256
	v_pk_mul_f32 v[182:183], v[110:111], v[164:165]
	v_pk_mul_f32 v[194:195], v[106:107], v[160:161]
	v_pk_mul_f32 v[190:191], v[108:109], v[166:167]
	v_pk_mul_f32 v[192:193], v[104:105], v[162:163]
	v_cvt_pk_bf16_f32 v190, v190, v191
	v_cvt_pk_bf16_f32 v191, v182, v183
	v_add_co_u32_e32 v182, vcc, s1, v176
	v_cvt_pk_bf16_f32 v192, v192, v193
	v_cvt_pk_bf16_f32 v193, v194, v195
	v_pk_mul_f32 v[194:195], v[74:75], v[168:169]
	s_nop 0
	v_addc_co_u32_e32 v183, vcc, 0, v177, vcc
	global_store_dwordx4 v[182:183], v[190:193], off
	v_pk_mul_f32 v[196:197], v[72:73], v[170:171]
	s_mov_b32 s1, 0x30000
	v_pk_mul_f32 v[190:191], v[76:77], v[174:175]
	v_pk_mul_f32 v[192:193], v[78:79], v[172:173]
	v_cvt_pk_bf16_f32 v190, v190, v191
	s_nop 0
	v_cvt_pk_bf16_f32 v191, v192, v193
	v_cvt_pk_bf16_f32 v192, v196, v197
	v_cvt_pk_bf16_f32 v193, v194, v195
	global_store_dwordx4 v[182:183], v[190:193], off offset:256
	v_pk_mul_f32 v[182:183], v[102:103], v[164:165]
	v_pk_mul_f32 v[194:195], v[98:99], v[160:161]
	v_pk_mul_f32 v[190:191], v[100:101], v[166:167]
	v_pk_mul_f32 v[192:193], v[96:97], v[162:163]
	v_cvt_pk_bf16_f32 v190, v190, v191
	v_cvt_pk_bf16_f32 v191, v182, v183
	v_add_co_u32_e32 v182, vcc, s1, v176
	v_cvt_pk_bf16_f32 v192, v192, v193
	v_cvt_pk_bf16_f32 v193, v194, v195
	v_pk_mul_f32 v[194:195], v[66:67], v[168:169]
	s_nop 0
	v_addc_co_u32_e32 v183, vcc, 0, v177, vcc
	global_store_dwordx4 v[182:183], v[190:193], off
	v_pk_mul_f32 v[196:197], v[64:65], v[170:171]
	s_mov_b32 s1, 0x80000
	v_pk_mul_f32 v[190:191], v[68:69], v[174:175]
	v_pk_mul_f32 v[192:193], v[70:71], v[172:173]
	v_cvt_pk_bf16_f32 v190, v190, v191
	s_nop 0
	v_cvt_pk_bf16_f32 v191, v192, v193
	v_cvt_pk_bf16_f32 v192, v196, v197
; __device__ __forceinline__ unsigned cvt_pk_bf16(float lo, float hi) { unsigned r; asm volatile("v_cvt_pk_bf16_f32 %0, %1, %2" : "=v"(r) : "v"(lo), "v"(hi)); return r; }
;     __device__ __forceinline__ void operator()(const f32x4 (&acc)[2][2][4][2], const Unit& u, int wr, int wc, int fr, int fq) const {
;     ...
; #pragma unroll
;         for (int ai = 0; ai < 2; ++ai)
; #pragma unroll
;             for (int m = 0; m < 4; ++m)
; #pragma unroll
;                 for (int bj = 0; bj < 2; ++bj) { const f32x4 v0 = gv[bj][0] * acc[ai][bj][m][0], v1 = gv[bj][1] * acc[ai][bj][m][1];
;                     u32x4 w; w.x = cvt_pk_bf16(v0[0], v0[1]); w.y = cvt_pk_bf16(v0[2], v0[3]); w.z = cvt_pk_bf16(v1[0], v1[1]); w.w = cvt_pk_bf16(v1[2], v1[3]);
;                     *(u32x4*)(dbase + (size_t)(ai * HALF + m * 16) * 2048 + bj * HALF) = w; }
	v_cvt_pk_bf16_f32 v193, v194, v195
	global_store_dwordx4 v[182:183], v[190:193], off offset:256
	v_pk_mul_f32 v[182:183], v[62:63], v[164:165]
	v_pk_mul_f32 v[194:195], v[58:59], v[160:161]
	v_pk_mul_f32 v[190:191], v[60:61], v[166:167]
	v_pk_mul_f32 v[192:193], v[56:57], v[162:163]
	v_cvt_pk_bf16_f32 v190, v190, v191
	v_cvt_pk_bf16_f32 v191, v182, v183
	v_add_co_u32_e32 v182, vcc, s1, v176
	v_cvt_pk_bf16_f32 v192, v192, v193
	v_cvt_pk_bf16_f32 v193, v194, v195
	v_pk_mul_f32 v[194:195], v[26:27], v[168:169]
	s_nop 0
	v_addc_co_u32_e32 v183, vcc, 0, v177, vcc
	global_store_dwordx4 v[182:183], v[190:193], off
	v_pk_mul_f32 v[196:197], v[24:25], v[170:171]
	s_mov_b32 s1, 0x90000
	v_pk_mul_f32 v[190:191], v[28:29], v[174:175]
	v_pk_mul_f32 v[192:193], v[30:31], v[172:173]
	v_cvt_pk_bf16_f32 v190, v190, v191
	s_nop 0
	v_cvt_pk_bf16_f32 v191, v192, v193
	v_cvt_pk_bf16_f32 v192, v196, v197
	v_cvt_pk_bf16_f32 v193, v194, v195
	global_store_dwordx4 v[182:183], v[190:193], off offset:256
	v_pk_mul_f32 v[182:183], v[54:55], v[164:165]
	v_pk_mul_f32 v[194:195], v[50:51], v[160:161]
	v_pk_mul_f32 v[190:191], v[52:53], v[166:167]
	v_pk_mul_f32 v[192:193], v[48:49], v[162:163]
	v_cvt_pk_bf16_f32 v190, v190, v191
	v_cvt_pk_bf16_f32 v191, v182, v183
	v_add_co_u32_e32 v182, vcc, s1, v176
	v_cvt_pk_bf16_f32 v192, v192, v193
	v_cvt_pk_bf16_f32 v193, v194, v195
	v_pk_mul_f32 v[194:195], v[18:19], v[168:169]
	s_nop 0
	v_addc_co_u32_e32 v183, vcc, 0, v177, vcc
	global_store_dwordx4 v[182:183], v[190:193], off
	v_pk_mul_f32 v[196:197], v[16:17], v[170:171]
	s_mov_b32 s1, 0xa0000
	v_pk_mul_f32 v[190:191], v[20:21], v[174:175]
	v_pk_mul_f32 v[192:193], v[22:23], v[172:173]
	v_cvt_pk_bf16_f32 v190, v190, v191
	s_nop 0
	v_cvt_pk_bf16_f32 v191, v192, v193
	v_cvt_pk_bf16_f32 v192, v196, v197
	v_cvt_pk_bf16_f32 v193, v194, v195
	global_store_dwordx4 v[182:183], v[190:193], off offset:256
	v_pk_mul_f32 v[182:183], v[46:47], v[164:165]
	v_pk_mul_f32 v[194:195], v[42:43], v[160:161]
	v_pk_mul_f32 v[190:191], v[44:45], v[166:167]
	v_pk_mul_f32 v[192:193], v[40:41], v[162:163]
	v_cvt_pk_bf16_f32 v190, v190, v191
	v_cvt_pk_bf16_f32 v191, v182, v183
	v_add_co_u32_e32 v182, vcc, s1, v176
	v_cvt_pk_bf16_f32 v192, v192, v193
	v_cvt_pk_bf16_f32 v193, v194, v195
	v_pk_mul_f32 v[164:165], v[38:39], v[164:165]
	s_nop 0
	v_addc_co_u32_e32 v183, vcc, 0, v177, vcc
	global_store_dwordx4 v[182:183], v[190:193], off
	s_mov_b32 s1, 0xb0000
	v_pk_mul_f32 v[194:195], v[10:11], v[168:169]
	v_pk_mul_f32 v[192:193], v[14:15], v[172:173]
	v_pk_mul_f32 v[190:191], v[12:13], v[174:175]
	v_pk_mul_f32 v[196:197], v[8:9], v[170:171]
	v_cvt_pk_bf16_f32 v190, v190, v191
	v_cvt_pk_bf16_f32 v191, v192, v193
	v_pk_mul_f32 v[166:167], v[36:37], v[166:167]
	v_cvt_pk_bf16_f32 v192, v196, v197
	v_cvt_pk_bf16_f32 v193, v194, v195
	global_store_dwordx4 v[182:183], v[190:193], off offset:256
	v_pk_mul_f32 v[182:183], v[34:35], v[160:161]
	v_pk_mul_f32 v[162:163], v[32:33], v[162:163]
	v_cvt_pk_bf16_f32 v160, v166, v167
	v_cvt_pk_bf16_f32 v161, v164, v165
	v_add_co_u32_e32 v164, vcc, s1, v176
	v_cvt_pk_bf16_f32 v162, v162, v163
	v_cvt_pk_bf16_f32 v163, v182, v183
	v_pk_mul_f32 v[166:167], v[2:3], v[168:169]
	s_nop 0
	v_addc_co_u32_e32 v165, vcc, 0, v177, vcc
	global_store_dwordx4 v[164:165], v[160:163], off
	v_pk_mul_f32 v[168:169], v[0:1], v[170:171]
	s_nop 0
	v_pk_mul_f32 v[162:163], v[6:7], v[172:173]
	v_pk_mul_f32 v[160:161], v[4:5], v[174:175]
	s_nop 0
	v_cvt_pk_bf16_f32 v160, v160, v161
	v_cvt_pk_bf16_f32 v161, v162, v163
	v_cvt_pk_bf16_f32 v162, v168, v169
	v_cvt_pk_bf16_f32 v163, v166, v167
	global_store_dwordx4 v[164:165], v[160:163], off offset:256
